# P8 sample w_out GEMM split in K over 32 workgroups with one write-back + flag per writer workgroup (P12 flags generation 2)
# speedup vs baseline: 1.0043x; 1.0043x over previous
; #define PG8_STAGE(bufoff, gbase, voff) do { _Pragma("unroll") for (int _i = 0; _i < 2; ++_i) \
;         __builtin_amdgcn_global_load_lds((const unsigned*)((const char*)(gbase) + (voff)[_i]), (PG8_LAS unsigned*)(lds + (bufoff) + ldsw + _i * 8192), 16, 0, 0); } while (0)
; #define PG8_LDA(dst, b, h) do { _Pragma("unroll") for (int m = 0; m < 4; ++m) _Pragma("unroll") for (int k = 0; k < 2; ++k) dst[m][k] = *(const PG8_LAS bf16x8*)(lds + PG8_SA(b, h) + aoff + m * 2048 + k * 1024); } while (0)
; #define PG8_LDB(dst, b, h) do { _Pragma("unroll") for (int n = 0; n < 2; ++n) _Pragma("unroll") for (int k = 0; k < 2; ++k) dst[n][k] = *(const PG8_LAS bf16x8*)(lds + PG8_SB(b, h) + boff + n * 2048 + k * 1024); } while (0)
; #define PG8_MMA(ai, bj, At, Bt) do { __builtin_amdgcn_s_setprio(1); _Pragma("unroll") for (int m = 0; m < 4; ++m) _Pragma("unroll") for (int n = 0; n < 2; ++n) _Pragma("unroll") for (int k = 0; k < 2; ++k) \
;         acc[ai][bj][m][n] = __builtin_amdgcn_mfma_f32_16x16x32_bf16(Bt[n][k], At[m][k], acc[ai][bj][m][n], 0, 0, 0); __builtin_amdgcn_s_setprio(0); } while (0)
; #define PG8_WAIT_V(n) asm volatile("s_waitcnt vmcnt(" #n ")" ::: "memory")
; #define PG8_WAIT_L(n) asm volatile("s_waitcnt lgkmcnt(" #n ")" ::: "memory")
; #define PG8_BAR __builtin_amdgcn_s_barrier()
; #define PG8_SCHED __builtin_amdgcn_sched_barrier(0)
; template <class Epi, class Sched, bool ALIGN_EPI = false, bool SP2 = false>
; __device__ __forceinline__ void gemm_phase(PG8_LAS unsigned char* lds, const Gemm g, const Sched& S, const Epi& E) {
;     ...
;         for (int t = 0; t < nt; t += 2) {
;             const bool last = (t == nt - 2);
;             const char* a1 = cA + (size_t)(t + 1) * kstep;
;             const char* a2 = last ? nA : cA + (size_t)(t + 2) * kstep; const char* b2 = last ? nB : cB + (size_t)(t + 2) * kstep;
;             const char* a3 = a2 + kstep; const char* b3 = b2 + kstep;
;             if (last && has_next) S.a_ready(nxt);
;             if constexpr (SP2) {
;             PG8_LDB(B0, 0, 0); PG8_LDB(B1, 0, 1); PG8_SCHED; PG8_LDA(At, 0, 0); PG8_STAGE(PG8_SA(1, 1), a1 + hstep, voffA);
;             PG8_WAIT_V(8); PG8_WAIT_L(0); PG8_BAR; PG8_MMA(0, 0, At, B0); PG8_MMA(0, 1, At, B1); PG8_BAR; PG8_SCHED;
;             PG8_LDA(At, 0, 1); PG8_STAGE(PG8_SB(0, 0), b2, voffB); PG8_STAGE(PG8_SB(0, 1), b2 + hstep, voffB); PG8_STAGE(PG8_SA(0, 0), a2, voffA);
.LBB0_1059:
	ds_read_b128 v[136:139], v143
	ds_read_b128 v[148:151], v143 offset:1024
	ds_read_b128 v[152:155], v143 offset:2048
	ds_read_b128 v[156:159], v143 offset:3072
	ds_read_b128 v[160:163], v144
	ds_read_b128 v[164:167], v144 offset:1024
	ds_read_b128 v[168:171], v144 offset:2048
	ds_read_b128 v[172:175], v144 offset:3072
	s_add_u32 s3, s28, 0xfffc0080
	s_addc_u32 s30, s29, -1
	s_cmp_eq_u32 s71, 4
	s_cselect_b32 s35, s21, s30
	s_cselect_b32 s34, s67, s3
	s_cselect_b32 s31, s19, s70
	s_cselect_b32 s30, s68, s69
	v_lshl_add_u64 v[212:213], s[28:29], 0, v[132:133]
	s_add_i32 m0, s47, 0xc000
	ds_read_b128 v[180:183], v145
	ds_read_b128 v[184:187], v145 offset:1024
	ds_read_b128 v[188:191], v145 offset:2048
	ds_read_b128 v[192:195], v145 offset:3072
	ds_read_b128 v[196:199], v145 offset:4096
	ds_read_b128 v[200:203], v145 offset:5120
	ds_read_b128 v[204:207], v145 offset:6144
	ds_read_b128 v[208:211], v145 offset:7168
	global_load_lds_dwordx4 v[212:213], off
	v_lshl_add_u64 v[212:213], s[28:29], 0, v[134:135]
	s_add_i32 m0, s47, 0xe000
	s_nop 0
	global_load_lds_dwordx4 v[212:213], off
	s_waitcnt vmcnt(8)
	s_waitcnt lgkmcnt(0)
	s_barrier
	s_setprio 1
	s_waitcnt lgkmcnt(0)
	v_mfma_f32_16x16x32_bf16 v[124:127], v[136:139], v[180:183], v[124:127]
	v_mfma_f32_16x16x32_bf16 v[120:123], v[152:155], v[180:183], v[120:123]
	v_mfma_f32_16x16x32_bf16 v[112:115], v[136:139], v[188:191], v[112:115]
	v_mfma_f32_16x16x32_bf16 v[104:107], v[152:155], v[188:191], v[104:107]
	v_mfma_f32_16x16x32_bf16 v[96:99], v[136:139], v[196:199], v[96:99]
	v_mfma_f32_16x16x32_bf16 v[88:91], v[152:155], v[196:199], v[88:91]
	v_mfma_f32_16x16x32_bf16 v[80:83], v[136:139], v[204:207], v[80:83]
	v_mfma_f32_16x16x32_bf16 v[72:75], v[152:155], v[204:207], v[72:75]
	v_mfma_f32_16x16x32_bf16 v[124:127], v[148:151], v[184:187], v[124:127]
	v_mfma_f32_16x16x32_bf16 v[120:123], v[156:159], v[184:187], v[120:123]
	v_mfma_f32_16x16x32_bf16 v[112:115], v[148:151], v[192:195], v[112:115]
	v_mfma_f32_16x16x32_bf16 v[104:107], v[156:159], v[192:195], v[104:107]
	v_mfma_f32_16x16x32_bf16 v[96:99], v[148:151], v[200:203], v[96:99]
	v_mfma_f32_16x16x32_bf16 v[88:91], v[156:159], v[200:203], v[88:91]
	v_mfma_f32_16x16x32_bf16 v[80:83], v[148:151], v[208:211], v[80:83]
	v_mfma_f32_16x16x32_bf16 v[72:75], v[156:159], v[208:211], v[72:75]
	s_setprio 0
	s_setprio 1
	v_mfma_f32_16x16x32_bf16 v[116:119], v[160:163], v[180:183], v[116:119]
	v_mfma_f32_16x16x32_bf16 v[108:111], v[168:171], v[180:183], v[108:111]
	v_mfma_f32_16x16x32_bf16 v[100:103], v[160:163], v[188:191], v[100:103]
	v_mfma_f32_16x16x32_bf16 v[92:95], v[168:171], v[188:191], v[92:95]
	v_mfma_f32_16x16x32_bf16 v[84:87], v[160:163], v[196:199], v[84:87]
	v_mfma_f32_16x16x32_bf16 v[76:79], v[168:171], v[196:199], v[76:79]
	v_mfma_f32_16x16x32_bf16 v[68:71], v[160:163], v[204:207], v[68:71]
	v_mfma_f32_16x16x32_bf16 v[64:67], v[168:171], v[204:207], v[64:67]
	v_mfma_f32_16x16x32_bf16 v[116:119], v[164:167], v[184:187], v[116:119]
	v_mfma_f32_16x16x32_bf16 v[108:111], v[172:175], v[184:187], v[108:111]
	v_mfma_f32_16x16x32_bf16 v[100:103], v[164:167], v[192:195], v[100:103]
	v_mfma_f32_16x16x32_bf16 v[92:95], v[172:175], v[192:195], v[92:95]
	v_mfma_f32_16x16x32_bf16 v[84:87], v[164:167], v[200:203], v[84:87]
	v_mfma_f32_16x16x32_bf16 v[76:79], v[172:175], v[200:203], v[76:79]
	v_mfma_f32_16x16x32_bf16 v[68:71], v[164:167], v[208:211], v[68:71]
	v_mfma_f32_16x16x32_bf16 v[64:67], v[172:175], v[208:211], v[64:67]
	s_setprio 0
	s_barrier
	s_add_i32 s3, s65, s46
	v_lshl_add_u64 v[212:213], s[30:31], 0, v[128:129]
	s_mov_b32 m0, s3
	ds_read_b128 v[180:183], v145 offset:16384
	ds_read_b128 v[184:187], v145 offset:17408
	ds_read_b128 v[188:191], v145 offset:18432
	ds_read_b128 v[192:195], v145 offset:19456
	ds_read_b128 v[196:199], v145 offset:20480
	ds_read_b128 v[200:203], v145 offset:21504
	ds_read_b128 v[204:207], v145 offset:22528
	ds_read_b128 v[208:211], v145 offset:23552
	global_load_lds_dwordx4 v[212:213], off
	s_add_i32 m0, s3, 0x2000
	s_add_u32 s36, s30, 0x40000
	v_lshl_add_u64 v[214:215], s[30:31], 0, v[130:131]
	s_addc_u32 s37, s31, 0
	s_add_i32 s3, s66, s46
	global_load_lds_dwordx4 v[214:215], off
	v_lshl_add_u64 v[216:217], s[36:37], 0, v[128:129]
	s_mov_b32 m0, s3
	v_lshl_add_u64 v[218:219], s[34:35], 0, v[130:131]
	global_load_lds_dwordx4 v[216:217], off
	v_lshl_add_u64 v[216:217], s[36:37], 0, v[130:131]
	s_add_i32 m0, s3, 0x2000
	s_nop 0
	global_load_lds_dwordx4 v[216:217], off
	v_lshl_add_u64 v[216:217], s[34:35], 0, v[128:129]
	s_mov_b32 m0, s47
	s_nop 0
	global_load_lds_dwordx4 v[216:217], off
	s_mov_b32 m0, s60
	s_nop 0
	global_load_lds_dwordx4 v[218:219], off
	s_waitcnt vmcnt(8)
	s_waitcnt lgkmcnt(0)
	s_barrier
; #define PG8_STAGE(bufoff, gbase, voff) do { _Pragma("unroll") for (int _i = 0; _i < 2; ++_i) \
;         __builtin_amdgcn_global_load_lds((const unsigned*)((const char*)(gbase) + (voff)[_i]), (PG8_LAS unsigned*)(lds + (bufoff) + ldsw + _i * 8192), 16, 0, 0); } while (0)
; #define PG8_LDA(dst, b, h) do { _Pragma("unroll") for (int m = 0; m < 4; ++m) _Pragma("unroll") for (int k = 0; k < 2; ++k) dst[m][k] = *(const PG8_LAS bf16x8*)(lds + PG8_SA(b, h) + aoff + m * 2048 + k * 1024); } while (0)
; #define PG8_LDB(dst, b, h) do { _Pragma("unroll") for (int n = 0; n < 2; ++n) _Pragma("unroll") for (int k = 0; k < 2; ++k) dst[n][k] = *(const PG8_LAS bf16x8*)(lds + PG8_SB(b, h) + boff + n * 2048 + k * 1024); } while (0)
; #define PG8_MMA(ai, bj, At, Bt) do { __builtin_amdgcn_s_setprio(1); _Pragma("unroll") for (int m = 0; m < 4; ++m) _Pragma("unroll") for (int n = 0; n < 2; ++n) _Pragma("unroll") for (int k = 0; k < 2; ++k) \
;         acc[ai][bj][m][n] = __builtin_amdgcn_mfma_f32_16x16x32_bf16(Bt[n][k], At[m][k], acc[ai][bj][m][n], 0, 0, 0); __builtin_amdgcn_s_setprio(0); } while (0)
; #define PG8_WAIT_V(n) asm volatile("s_waitcnt vmcnt(" #n ")" ::: "memory")
; #define PG8_WAIT_L(n) asm volatile("s_waitcnt lgkmcnt(" #n ")" ::: "memory")
; #define PG8_BAR __builtin_amdgcn_s_barrier()
; #define PG8_SCHED __builtin_amdgcn_sched_barrier(0)
; template <class Epi, class Sched, bool ALIGN_EPI = false, bool SP2 = false>
; __device__ __forceinline__ void gemm_phase(PG8_LAS unsigned char* lds, const Gemm g, const Sched& S, const Epi& E) {
;     ...
;             PG8_WAIT_V(8); PG8_WAIT_L(0); PG8_BAR; PG8_MMA(1, 0, At, B0); PG8_MMA(1, 1, At, B1); PG8_BAR; PG8_SCHED;
;             PG8_LDB(B0, 1, 0); PG8_LDB(B1, 1, 1); PG8_SCHED; PG8_LDA(At, 1, 0); PG8_STAGE(PG8_SA(0, 1), a2 + hstep, voffA);
;             PG8_WAIT_V(8); PG8_WAIT_L(0); PG8_BAR; PG8_MMA(0, 0, At, B0); PG8_MMA(0, 1, At, B1); PG8_BAR; PG8_SCHED;
	s_setprio 1
	s_waitcnt lgkmcnt(0)
	v_mfma_f32_16x16x32_bf16 v[60:63], v[136:139], v[180:183], v[60:63]
	v_mfma_f32_16x16x32_bf16 v[56:59], v[152:155], v[180:183], v[56:59]
	v_mfma_f32_16x16x32_bf16 v[48:51], v[136:139], v[188:191], v[48:51]
	v_mfma_f32_16x16x32_bf16 v[40:43], v[152:155], v[188:191], v[40:43]
	v_mfma_f32_16x16x32_bf16 v[32:35], v[136:139], v[196:199], v[32:35]
	v_mfma_f32_16x16x32_bf16 v[24:27], v[152:155], v[196:199], v[24:27]
	v_mfma_f32_16x16x32_bf16 v[16:19], v[136:139], v[204:207], v[16:19]
	v_mfma_f32_16x16x32_bf16 v[8:11], v[152:155], v[204:207], v[8:11]
	v_mfma_f32_16x16x32_bf16 v[60:63], v[148:151], v[184:187], v[60:63]
	v_mfma_f32_16x16x32_bf16 v[56:59], v[156:159], v[184:187], v[56:59]
	v_mfma_f32_16x16x32_bf16 v[48:51], v[148:151], v[192:195], v[48:51]
	v_mfma_f32_16x16x32_bf16 v[40:43], v[156:159], v[192:195], v[40:43]
	v_mfma_f32_16x16x32_bf16 v[32:35], v[148:151], v[200:203], v[32:35]
	v_mfma_f32_16x16x32_bf16 v[24:27], v[156:159], v[200:203], v[24:27]
	v_mfma_f32_16x16x32_bf16 v[16:19], v[148:151], v[208:211], v[16:19]
	v_mfma_f32_16x16x32_bf16 v[8:11], v[156:159], v[208:211], v[8:11]
	s_setprio 0
	s_setprio 1
	v_mfma_f32_16x16x32_bf16 v[52:55], v[160:163], v[180:183], v[52:55]
	v_mfma_f32_16x16x32_bf16 v[44:47], v[168:171], v[180:183], v[44:47]
	v_mfma_f32_16x16x32_bf16 v[36:39], v[160:163], v[188:191], v[36:39]
	v_mfma_f32_16x16x32_bf16 v[28:31], v[168:171], v[188:191], v[28:31]
	v_mfma_f32_16x16x32_bf16 v[20:23], v[160:163], v[196:199], v[20:23]
	v_mfma_f32_16x16x32_bf16 v[12:15], v[168:171], v[196:199], v[12:15]
	v_mfma_f32_16x16x32_bf16 v[4:7], v[160:163], v[204:207], v[4:7]
	v_mfma_f32_16x16x32_bf16 v[0:3], v[168:171], v[204:207], v[0:3]
	v_mfma_f32_16x16x32_bf16 v[52:55], v[164:167], v[184:187], v[52:55]
	v_mfma_f32_16x16x32_bf16 v[44:47], v[172:175], v[184:187], v[44:47]
	v_mfma_f32_16x16x32_bf16 v[36:39], v[164:167], v[192:195], v[36:39]
	v_mfma_f32_16x16x32_bf16 v[28:31], v[172:175], v[192:195], v[28:31]
	v_mfma_f32_16x16x32_bf16 v[20:23], v[164:167], v[200:203], v[20:23]
	v_mfma_f32_16x16x32_bf16 v[12:15], v[172:175], v[200:203], v[12:15]
	v_mfma_f32_16x16x32_bf16 v[4:7], v[164:167], v[208:211], v[4:7]
	v_mfma_f32_16x16x32_bf16 v[0:3], v[172:175], v[208:211], v[0:3]
	s_setprio 0
	s_barrier
	s_add_i32 s3, 0, 0x18000
	v_add_u32_e32 v147, s3, v141
	s_add_i32 s33, 0, 0x1c000
	ds_read_b128 v[136:139], v147
	ds_read_b128 v[148:151], v147 offset:1024
	ds_read_b128 v[152:155], v147 offset:2048
	ds_read_b128 v[156:159], v147 offset:3072
	v_add_u32_e32 v147, s33, v141
	ds_read_b128 v[160:163], v147
	ds_read_b128 v[164:167], v147 offset:1024
	ds_read_b128 v[168:171], v147 offset:2048
	ds_read_b128 v[172:175], v147 offset:3072
	s_add_u32 s34, s34, 0x40000
	s_addc_u32 s35, s35, 0
	s_mov_b32 m0, s61
	v_lshl_add_u64 v[220:221], s[34:35], 0, v[128:129]
	ds_read_b128 v[180:183], v145 offset:32768
	ds_read_b128 v[184:187], v145 offset:33792
	ds_read_b128 v[188:191], v145 offset:34816
	ds_read_b128 v[192:195], v145 offset:35840
	ds_read_b128 v[196:199], v145 offset:36864
	ds_read_b128 v[200:203], v145 offset:37888
	ds_read_b128 v[204:207], v145 offset:38912
	ds_read_b128 v[208:211], v145 offset:39936
	global_load_lds_dwordx4 v[220:221], off
	v_lshl_add_u64 v[220:221], s[34:35], 0, v[130:131]
	s_mov_b32 m0, s62
	s_nop 0
	global_load_lds_dwordx4 v[220:221], off
	s_waitcnt vmcnt(8)
	s_waitcnt lgkmcnt(0)
	s_barrier
	s_setprio 1
	s_waitcnt lgkmcnt(0)
	v_mfma_f32_16x16x32_bf16 v[124:127], v[136:139], v[180:183], v[124:127]
	v_mfma_f32_16x16x32_bf16 v[120:123], v[152:155], v[180:183], v[120:123]
	v_mfma_f32_16x16x32_bf16 v[112:115], v[136:139], v[188:191], v[112:115]
	v_mfma_f32_16x16x32_bf16 v[104:107], v[152:155], v[188:191], v[104:107]
	v_mfma_f32_16x16x32_bf16 v[96:99], v[136:139], v[196:199], v[96:99]
	v_mfma_f32_16x16x32_bf16 v[88:91], v[152:155], v[196:199], v[88:91]
	v_mfma_f32_16x16x32_bf16 v[80:83], v[136:139], v[204:207], v[80:83]
	v_mfma_f32_16x16x32_bf16 v[72:75], v[152:155], v[204:207], v[72:75]
	v_mfma_f32_16x16x32_bf16 v[124:127], v[148:151], v[184:187], v[124:127]
	v_mfma_f32_16x16x32_bf16 v[120:123], v[156:159], v[184:187], v[120:123]
	v_mfma_f32_16x16x32_bf16 v[112:115], v[148:151], v[192:195], v[112:115]
	v_mfma_f32_16x16x32_bf16 v[104:107], v[156:159], v[192:195], v[104:107]
	v_mfma_f32_16x16x32_bf16 v[96:99], v[148:151], v[200:203], v[96:99]
	v_mfma_f32_16x16x32_bf16 v[88:91], v[156:159], v[200:203], v[88:91]
	v_mfma_f32_16x16x32_bf16 v[80:83], v[148:151], v[208:211], v[80:83]
	v_mfma_f32_16x16x32_bf16 v[72:75], v[156:159], v[208:211], v[72:75]
	s_setprio 0
	s_setprio 1
	v_mfma_f32_16x16x32_bf16 v[116:119], v[160:163], v[180:183], v[116:119]
	v_mfma_f32_16x16x32_bf16 v[108:111], v[168:171], v[180:183], v[108:111]
	v_mfma_f32_16x16x32_bf16 v[100:103], v[160:163], v[188:191], v[100:103]
	v_mfma_f32_16x16x32_bf16 v[92:95], v[168:171], v[188:191], v[92:95]
	v_mfma_f32_16x16x32_bf16 v[84:87], v[160:163], v[196:199], v[84:87]
	v_mfma_f32_16x16x32_bf16 v[76:79], v[168:171], v[196:199], v[76:79]
	v_mfma_f32_16x16x32_bf16 v[68:71], v[160:163], v[204:207], v[68:71]
	v_mfma_f32_16x16x32_bf16 v[64:67], v[168:171], v[204:207], v[64:67]
	v_mfma_f32_16x16x32_bf16 v[116:119], v[164:167], v[184:187], v[116:119]
	v_mfma_f32_16x16x32_bf16 v[108:111], v[172:175], v[184:187], v[108:111]
	v_mfma_f32_16x16x32_bf16 v[100:103], v[164:167], v[192:195], v[100:103]
	v_mfma_f32_16x16x32_bf16 v[92:95], v[172:175], v[192:195], v[92:95]
	v_mfma_f32_16x16x32_bf16 v[84:87], v[164:167], v[200:203], v[84:87]
	v_mfma_f32_16x16x32_bf16 v[76:79], v[172:175], v[200:203], v[76:79]
	v_mfma_f32_16x16x32_bf16 v[68:71], v[164:167], v[208:211], v[68:71]
	v_mfma_f32_16x16x32_bf16 v[64:67], v[172:175], v[208:211], v[64:67]
	s_setprio 0
	s_barrier
; #define PG8_STAGE(bufoff, gbase, voff) do { _Pragma("unroll") for (int _i = 0; _i < 2; ++_i) \
;         __builtin_amdgcn_global_load_lds((const unsigned*)((const char*)(gbase) + (voff)[_i]), (PG8_LAS unsigned*)(lds + (bufoff) + ldsw + _i * 8192), 16, 0, 0); } while (0)
; #define PG8_LDA(dst, b, h) do { _Pragma("unroll") for (int m = 0; m < 4; ++m) _Pragma("unroll") for (int k = 0; k < 2; ++k) dst[m][k] = *(const PG8_LAS bf16x8*)(lds + PG8_SA(b, h) + aoff + m * 2048 + k * 1024); } while (0)
; #define PG8_MMA(ai, bj, At, Bt) do { __builtin_amdgcn_s_setprio(1); _Pragma("unroll") for (int m = 0; m < 4; ++m) _Pragma("unroll") for (int n = 0; n < 2; ++n) _Pragma("unroll") for (int k = 0; k < 2; ++k) \
;         acc[ai][bj][m][n] = __builtin_amdgcn_mfma_f32_16x16x32_bf16(Bt[n][k], At[m][k], acc[ai][bj][m][n], 0, 0, 0); __builtin_amdgcn_s_setprio(0); } while (0)
; #define PG8_WAIT_V(n) asm volatile("s_waitcnt vmcnt(" #n ")" ::: "memory")
; #define PG8_WAIT_L(n) asm volatile("s_waitcnt lgkmcnt(" #n ")" ::: "memory")
; #define PG8_BAR __builtin_amdgcn_s_barrier()
; #define PG8_SCHED __builtin_amdgcn_sched_barrier(0)
; template <class Epi, class Sched, bool ALIGN_EPI = false, bool SP2 = false>
; __device__ __forceinline__ void gemm_phase(PG8_LAS unsigned char* lds, const Gemm g, const Sched& S, const Epi& E) {
;     ...
;         for (int t = 0; t < nt; t += 2) {
;             const bool last = (t == nt - 2);
;             const char* a1 = cA + (size_t)(t + 1) * kstep;
;             const char* a2 = last ? nA : cA + (size_t)(t + 2) * kstep; const char* b2 = last ? nB : cB + (size_t)(t + 2) * kstep;
;     ...
;             PG8_LDA(At, 1, 1); PG8_STAGE(PG8_SB(1, 0), b3, voffB); PG8_STAGE(PG8_SB(1, 1), b3 + hstep, voffB); PG8_STAGE(PG8_SA(1, 0), a3, voffA);
;             PG8_WAIT_V(8); PG8_WAIT_L(0); PG8_BAR; PG8_MMA(1, 0, At, B0); PG8_MMA(1, 1, At, B1); PG8_BAR; PG8_SCHED;
	s_add_i32 s3, s3, s46
	v_lshl_add_u64 v[212:213], v[212:213], 0, s[14:15]
	s_mov_b32 m0, s3
	ds_read_b128 v[180:183], v145 offset:49152
	ds_read_b128 v[184:187], v145 offset:50176
	ds_read_b128 v[188:191], v145 offset:51200
	ds_read_b128 v[192:195], v145 offset:52224
	ds_read_b128 v[196:199], v145 offset:53248
	ds_read_b128 v[200:203], v145 offset:54272
	ds_read_b128 v[204:207], v145 offset:55296
	ds_read_b128 v[208:211], v145 offset:56320
	global_load_lds_dwordx4 v[212:213], off
	s_add_i32 m0, s3, 0x2000
	s_add_u32 s30, s30, 0x40080
	v_lshl_add_u64 v[212:213], v[214:215], 0, s[14:15]
	s_addc_u32 s31, s31, 0
	s_add_i32 s3, s33, s46
	global_load_lds_dwordx4 v[212:213], off
	v_lshl_add_u64 v[212:213], s[30:31], 0, v[128:129]
	s_mov_b32 m0, s3
	s_nop 0
	global_load_lds_dwordx4 v[212:213], off
	v_lshl_add_u64 v[212:213], s[30:31], 0, v[130:131]
	s_add_i32 m0, s3, 0x2000
	s_nop 0
	global_load_lds_dwordx4 v[212:213], off
	v_lshl_add_u64 v[212:213], v[216:217], 0, s[14:15]
	s_mov_b32 m0, s63
	s_nop 0
	global_load_lds_dwordx4 v[212:213], off
	v_lshl_add_u64 v[212:213], v[218:219], 0, s[14:15]
	s_mov_b32 m0, s64
	s_nop 0
	global_load_lds_dwordx4 v[212:213], off
	s_waitcnt vmcnt(8)
	s_waitcnt lgkmcnt(0)
	s_barrier
	s_setprio 1
	s_waitcnt lgkmcnt(0)
	v_mfma_f32_16x16x32_bf16 v[60:63], v[136:139], v[180:183], v[60:63]
	v_mfma_f32_16x16x32_bf16 v[56:59], v[152:155], v[180:183], v[56:59]
	v_mfma_f32_16x16x32_bf16 v[48:51], v[136:139], v[188:191], v[48:51]
	v_mfma_f32_16x16x32_bf16 v[40:43], v[152:155], v[188:191], v[40:43]
	v_mfma_f32_16x16x32_bf16 v[32:35], v[136:139], v[196:199], v[32:35]
	v_mfma_f32_16x16x32_bf16 v[24:27], v[152:155], v[196:199], v[24:27]
	v_mfma_f32_16x16x32_bf16 v[16:19], v[136:139], v[204:207], v[16:19]
	v_mfma_f32_16x16x32_bf16 v[8:11], v[152:155], v[204:207], v[8:11]
	v_mfma_f32_16x16x32_bf16 v[60:63], v[148:151], v[184:187], v[60:63]
	v_mfma_f32_16x16x32_bf16 v[56:59], v[156:159], v[184:187], v[56:59]
	v_mfma_f32_16x16x32_bf16 v[48:51], v[148:151], v[192:195], v[48:51]
	v_mfma_f32_16x16x32_bf16 v[40:43], v[156:159], v[192:195], v[40:43]
	v_mfma_f32_16x16x32_bf16 v[32:35], v[148:151], v[200:203], v[32:35]
	v_mfma_f32_16x16x32_bf16 v[24:27], v[156:159], v[200:203], v[24:27]
	v_mfma_f32_16x16x32_bf16 v[16:19], v[148:151], v[208:211], v[16:19]
	v_mfma_f32_16x16x32_bf16 v[8:11], v[156:159], v[208:211], v[8:11]
	s_setprio 0
	s_setprio 1
	v_mfma_f32_16x16x32_bf16 v[52:55], v[160:163], v[180:183], v[52:55]
	v_mfma_f32_16x16x32_bf16 v[44:47], v[168:171], v[180:183], v[44:47]
	v_mfma_f32_16x16x32_bf16 v[36:39], v[160:163], v[188:191], v[36:39]
	v_mfma_f32_16x16x32_bf16 v[28:31], v[168:171], v[188:191], v[28:31]
	v_mfma_f32_16x16x32_bf16 v[20:23], v[160:163], v[196:199], v[20:23]
	v_mfma_f32_16x16x32_bf16 v[12:15], v[168:171], v[196:199], v[12:15]
	v_mfma_f32_16x16x32_bf16 v[4:7], v[160:163], v[204:207], v[4:7]
	v_mfma_f32_16x16x32_bf16 v[0:3], v[168:171], v[204:207], v[0:3]
	v_mfma_f32_16x16x32_bf16 v[52:55], v[164:167], v[184:187], v[52:55]
	v_mfma_f32_16x16x32_bf16 v[44:47], v[172:175], v[184:187], v[44:47]
	v_mfma_f32_16x16x32_bf16 v[36:39], v[164:167], v[192:195], v[36:39]
	v_mfma_f32_16x16x32_bf16 v[28:31], v[172:175], v[192:195], v[28:31]
	v_mfma_f32_16x16x32_bf16 v[20:23], v[164:167], v[200:203], v[20:23]
	v_mfma_f32_16x16x32_bf16 v[12:15], v[172:175], v[200:203], v[12:15]
	v_mfma_f32_16x16x32_bf16 v[4:7], v[164:167], v[208:211], v[4:7]
	v_mfma_f32_16x16x32_bf16 v[0:3], v[172:175], v[208:211], v[0:3]
	s_setprio 0
	s_barrier
	s_add_i32 s71, s71, 2
	s_add_u32 s28, s28, 0x100
	s_addc_u32 s29, s29, 0
	s_add_u32 s69, s69, 0x100
	s_addc_u32 s70, s70, 0
	s_cmp_gt_u32 s71, 5
	s_cbranch_scc0 .LBB0_1059
; template <class Epi, class Sched, bool ALIGN_EPI = false, bool SP2 = false>
; __device__ __forceinline__ void gemm_phase(PG8_LAS unsigned char* lds, const Gemm g, const Sched& S, const Epi& E) {
;     ...
;         if constexpr (!Epi::AFTER_DRAIN) { E(acc, cur, wr, wc, fr, fq); S.done(cur); }
;         if (!has_next) break;
	s_and_b32 s100, s2, 15
	v_readfirstlane_b32 s101, v178
	s_lshl_b32 s98, s100, 18
	s_lshr_b32 s101, s101, 6
	s_lshl_b32 s99, s101, 15
	s_add_u32 s98, s98, s99
	s_lshl_b32 s100, s100, 2
	s_add_u32 s98, s54, s98
	s_addc_u32 s99, s55, 0
	s_add_u32 s98, s98, 0x2300000
	s_addc_u32 s99, s99, 0
	s_add_u32 s100, s54, s100
	s_addc_u32 s101, s55, 0
	s_add_u32 s100, s100, 0x22a2000
	s_addc_u32 s101, s101, 0
	v_lshlrev_b32_e32 v160, 4, v176
	v_mov_b32_e32 v161, 0
	s_cmp_lt_u32 s2, 16
	s_cbranch_scc1 .Lsk8_reader
	global_store_dwordx4 v160, v[0:3], s[98:99]
	s_add_u32 s98, s98, 0x400
	s_addc_u32 s99, s99, 0
	global_store_dwordx4 v160, v[4:7], s[98:99]
	s_add_u32 s98, s98, 0x400
	s_addc_u32 s99, s99, 0
	global_store_dwordx4 v160, v[8:11], s[98:99]
	s_add_u32 s98, s98, 0x400
	s_addc_u32 s99, s99, 0
	global_store_dwordx4 v160, v[12:15], s[98:99]
	s_add_u32 s98, s98, 0x400
	s_addc_u32 s99, s99, 0
	global_store_dwordx4 v160, v[16:19], s[98:99]
	s_add_u32 s98, s98, 0x400
	s_addc_u32 s99, s99, 0
	global_store_dwordx4 v160, v[20:23], s[98:99]
	s_add_u32 s98, s98, 0x400
	s_addc_u32 s99, s99, 0
	global_store_dwordx4 v160, v[24:27], s[98:99]
	s_add_u32 s98, s98, 0x400
	s_addc_u32 s99, s99, 0
	global_store_dwordx4 v160, v[28:31], s[98:99]
	s_add_u32 s98, s98, 0x400
	s_addc_u32 s99, s99, 0
	global_store_dwordx4 v160, v[32:35], s[98:99]
	s_add_u32 s98, s98, 0x400
	s_addc_u32 s99, s99, 0
	global_store_dwordx4 v160, v[36:39], s[98:99]
	s_add_u32 s98, s98, 0x400
	s_addc_u32 s99, s99, 0
	global_store_dwordx4 v160, v[40:43], s[98:99]
	s_add_u32 s98, s98, 0x400
	s_addc_u32 s99, s99, 0
	global_store_dwordx4 v160, v[44:47], s[98:99]
	s_add_u32 s98, s98, 0x400
	s_addc_u32 s99, s99, 0
	global_store_dwordx4 v160, v[48:51], s[98:99]
	s_add_u32 s98, s98, 0x400
	s_addc_u32 s99, s99, 0
	global_store_dwordx4 v160, v[52:55], s[98:99]
	s_add_u32 s98, s98, 0x400
	s_addc_u32 s99, s99, 0
	global_store_dwordx4 v160, v[56:59], s[98:99]
	s_add_u32 s98, s98, 0x400
	s_addc_u32 s99, s99, 0
	global_store_dwordx4 v160, v[60:63], s[98:99]
	s_add_u32 s98, s98, 0x400
	s_addc_u32 s99, s99, 0
	global_store_dwordx4 v160, v[64:67], s[98:99]
	s_add_u32 s98, s98, 0x400
	s_addc_u32 s99, s99, 0
	global_store_dwordx4 v160, v[68:71], s[98:99]
	s_add_u32 s98, s98, 0x400
	s_addc_u32 s99, s99, 0
	global_store_dwordx4 v160, v[72:75], s[98:99]
	s_add_u32 s98, s98, 0x400
	s_addc_u32 s99, s99, 0
	global_store_dwordx4 v160, v[76:79], s[98:99]
	s_add_u32 s98, s98, 0x400
	s_addc_u32 s99, s99, 0
	global_store_dwordx4 v160, v[80:83], s[98:99]
	s_add_u32 s98, s98, 0x400
	s_addc_u32 s99, s99, 0
	global_store_dwordx4 v160, v[84:87], s[98:99]
	s_add_u32 s98, s98, 0x400
	s_addc_u32 s99, s99, 0
	global_store_dwordx4 v160, v[88:91], s[98:99]
	s_add_u32 s98, s98, 0x400
	s_addc_u32 s99, s99, 0
	global_store_dwordx4 v160, v[92:95], s[98:99]
	s_add_u32 s98, s98, 0x400
	s_addc_u32 s99, s99, 0
	global_store_dwordx4 v160, v[96:99], s[98:99]
	s_add_u32 s98, s98, 0x400
	s_addc_u32 s99, s99, 0
	global_store_dwordx4 v160, v[100:103], s[98:99]
	s_add_u32 s98, s98, 0x400
	s_addc_u32 s99, s99, 0
	global_store_dwordx4 v160, v[104:107], s[98:99]
	s_add_u32 s98, s98, 0x400
	s_addc_u32 s99, s99, 0
	global_store_dwordx4 v160, v[108:111], s[98:99]
	s_add_u32 s98, s98, 0x400
	s_addc_u32 s99, s99, 0
	global_store_dwordx4 v160, v[112:115], s[98:99]
	s_add_u32 s98, s98, 0x400
	s_addc_u32 s99, s99, 0
	global_store_dwordx4 v160, v[116:119], s[98:99]
	s_add_u32 s98, s98, 0x400
	s_addc_u32 s99, s99, 0
	global_store_dwordx4 v160, v[120:123], s[98:99]
	s_add_u32 s98, s98, 0x400
	s_addc_u32 s99, s99, 0
	global_store_dwordx4 v160, v[124:127], s[98:99]
	s_add_u32 s98, s98, 0x400
	s_addc_u32 s99, s99, 0
	s_branch .LBB0_1051

; #define PG8_WAIT_V(n) asm volatile("s_waitcnt vmcnt(" #n ")" ::: "memory")
; #define PG8_BAR __builtin_amdgcn_s_barrier()
; template <class Epi, class Sched, bool ALIGN_EPI = false, bool SP2 = false>
; __device__ __forceinline__ void gemm_phase(PG8_LAS unsigned char* lds, const Gemm g, const Sched& S, const Epi& E) {
;     ...
;     PG8_WAIT_V(0);
;     if constexpr (!ALIGN_EPI) { if (wr == 0) PG8_BAR; }
;     PG8_BAR;
.LBB0_1076:
	s_waitcnt vmcnt(0)
	s_cmpk_gt_u32 s41, 0xff
	s_cbranch_scc1 .LBB0_1078
	s_barrier
.LBB0_1078:
	s_barrier
	s_cmp_lt_u32 s2, 16
	s_cbranch_scc1 .Lsk8_nowb
	v_cmp_eq_u32_e32 vcc, 0, v178
	s_and_saveexec_b64 s[0:1], vcc
	s_cbranch_execz .Lsk8_wbj
	buffer_wbl2 sc1
	s_waitcnt vmcnt(0)
	s_and_b32 s100, s2, 15
	s_lshl_b32 s100, s100, 2
	s_add_u32 s100, s54, s100
	s_addc_u32 s101, s55, 0
	s_add_u32 s100, s100, 0x22a2000
	s_addc_u32 s101, s101, 0
	v_mov_b32_e32 v161, 0
	v_mov_b32_e32 v162, 1
	global_atomic_add v161, v162, s[100:101]

; __device__ __forceinline__ unsigned xb_ld(unsigned* p)              { return __hip_atomic_load(p, __ATOMIC_RELAXED, __HIP_MEMORY_SCOPE_AGENT); }
; __device__ __forceinline__ unsigned xb_add(unsigned* p, unsigned v) { return __hip_atomic_fetch_add(p, v, __ATOMIC_RELAXED, __HIP_MEMORY_SCOPE_AGENT); }
; #define XB_SPIN(cond, bar) do { unsigned _sp = 0; while (cond) { __builtin_amdgcn_s_sleep(1); \
;     if ((++_sp & 255u) == 0u) { if (xb_ld(&(bar)[XB_TMO])) break; if (_sp > XB_SPIN_CAP) { atomicAdd(&(bar)[XB_TMO], 1u); break; } } } } while (0)
; __device__ __forceinline__ void xcd_barrier(const XcdBarrier& b) {
;     asm volatile("s_waitcnt vmcnt(0)" ::: "memory");
;     __syncthreads();
;     if (threadIdx.x == 0) {
;         unsigned* bar = b.bar;
;         __builtin_amdgcn_s_waitcnt(0);
;         unsigned nloc = b.st[0], nx = b.st[1];
;         if (nloc == 0u) { xcd_barrier_complete(bar, b.x, nloc, nx); b.st[0] = nloc; b.st[1] = nx; }
;         const unsigned old = xb_add(&bar[XB_XSUB(b.x)], 1u);
;         const unsigned gen = old / nloc;
;         if (old + 1u == (gen + 1u) * nloc) {
;             __builtin_amdgcn_fence(__ATOMIC_RELEASE, "agent");
;             asm volatile("s_waitcnt vmcnt(0)" ::: "memory");
;             const unsigned og = xb_add(&bar[XB_TOP], 1u);
;             const unsigned tg = og / nx;
;             if (og + 1u == (tg + 1u) * nx) xb_add(&bar[XB_TOPGEN], 1u);
;             else XB_SPIN(xb_ld(&bar[XB_TOPGEN]) == tg, bar);
;             __builtin_amdgcn_fence(__ATOMIC_ACQUIRE, "agent");
;             xb_add(&bar[XB_XGEN(b.x)], 1u);
;             asm volatile("s_waitcnt vmcnt(0)" ::: "memory");
;         } else {
;             XB_SPIN(xb_ld(&bar[XB_XGEN(b.x)]) == gen, bar);
;             __builtin_amdgcn_fence(__ATOMIC_ACQUIRE, "agent");
;             asm volatile("s_waitcnt vmcnt(0)" ::: "memory");
;         }
;     }
;     __syncthreads();
; }
.Lsk8_nowb:
.LBB0_1079:
	s_cmp_lt_i32 s56, 10
	s_cselect_b64 s[6:7], -1, 0
	s_cmp_gt_i32 s57, 9
	s_cselect_b64 s[0:1], -1, 0
	s_and_b64 s[0:1], s[6:7], s[0:1]
	s_andn2_b64 vcc, exec, s[0:1]
	s_cbranch_vccnz .LBB0_1139
	s_andn2_b64 vcc, exec, s[4:5]
	s_cbranch_vccnz .LBB0_1134
	s_getreg_b32 s3, hwreg(HW_REG_XCC_ID, 0, 4)
	s_waitcnt vmcnt(0)
	v_cmp_eq_u32_e32 vcc, 0, v178
	s_waitcnt vmcnt(0) lgkmcnt(0)
	s_barrier
	s_and_saveexec_b64 s[0:1], vcc
	s_cbranch_execz .LBB0_1133
	buffer_inv sc1
	v_mov_b32_e32 v0, 0x23ff0
	ds_read2_b32 v[0:1], v0 offset1:1
	s_and_b32 s98, s3, 15
	s_lshl_b32 s98, s98, 8
	s_add_u32 s98, s54, s98
	s_addc_u32 s99, s55, 0
	s_add_u32 s98, s98, 0x22a3400
	s_addc_u32 s99, s99, 0
	v_mov_b32_e32 v2, 0
	v_mov_b32_e32 v3, 1
	global_atomic_add v4, v2, v3, s[98:99] sc0
	s_add_u32 s100, s54, 0x22a5400
	s_addc_u32 s101, s55, 0
	s_waitcnt vmcnt(0) lgkmcnt(0)
	v_mul_u32_u24_e32 v0, 8, v0
	v_mul_u32_u24_e32 v1, 8, v1
	v_add_u32_e32 v4, 1, v4
	v_cmp_eq_u32_e32 vcc, v4, v0
	s_cbranch_vccz .Lxb_poll_s7
	buffer_wbl2 sc1
	s_waitcnt vmcnt(0)
	global_atomic_add v2, v3, s[100:101]
